# Y1: softmax dependent chains broken (row-max as two interleaved chains; exp stream interleaved with the row-sum adds from the start), on top of T1
# speedup vs baseline: 1.0155x; 1.0027x over previous
.LBB0_629:
	v_max_f32_e32 v148, v84, v85
	v_max_f32_e32 v149, v68, v69
	v_max3_f32 v148, v148, v86, v87
	v_max3_f32 v149, v149, v70, v71
	v_max3_f32 v148, v148, v88, v89
	v_max3_f32 v149, v149, v72, v73
	v_max3_f32 v148, v148, v90, v91
	v_max3_f32 v149, v149, v74, v75
	v_max3_f32 v148, v148, v92, v93
	v_max3_f32 v149, v149, v76, v77
	v_max3_f32 v148, v148, v94, v95
	v_max3_f32 v149, v149, v78, v79
	v_max3_f32 v148, v148, v96, v97
	v_max3_f32 v149, v149, v80, v81
	v_max3_f32 v148, v148, v98, v99
	v_max3_f32 v149, v149, v82, v83
	v_max_f32_e32 v148, v148, v149
	v_mov_b32_e32 v149, v148
	s_nop 1
	v_permlane32_swap_b32_e32 v148, v149
	v_max_f32_e32 v148, v148, v149
	v_sub_f32_e32 v149, v148, v182
	v_cmp_ge_f32_e32 vcc, s23, v149
	v_max_f32_e32 v148, v182, v148
	s_cmp_eq_u64 vcc, exec
	s_cselect_b64 vcc, -1, 0
	v_sub_f32_e32 v150, v182, v148
	v_cndmask_b32_e32 v182, v148, v182, vcc
	v_mul_f32_e32 v148, 0xbe0293ee, v182
	v_fmamk_f32 v84, v84, 0x3e0293ee, v148
	v_fmamk_f32 v85, v85, 0x3e0293ee, v148
	v_fmamk_f32 v86, v86, 0x3e0293ee, v148
	v_fmamk_f32 v87, v87, 0x3e0293ee, v148
	v_fmamk_f32 v88, v88, 0x3e0293ee, v148
	v_fmamk_f32 v89, v89, 0x3e0293ee, v148
	v_fmamk_f32 v90, v90, 0x3e0293ee, v148
	v_fmamk_f32 v91, v91, 0x3e0293ee, v148
	v_fmamk_f32 v92, v92, 0x3e0293ee, v148
	v_fmamk_f32 v93, v93, 0x3e0293ee, v148
	v_fmamk_f32 v94, v94, 0x3e0293ee, v148
	v_fmamk_f32 v95, v95, 0x3e0293ee, v148
	v_fmamk_f32 v96, v96, 0x3e0293ee, v148
	v_fmamk_f32 v97, v97, 0x3e0293ee, v148
	v_fmamk_f32 v98, v98, 0x3e0293ee, v148
	v_fmamk_f32 v99, v99, 0x3e0293ee, v148
	v_fmamk_f32 v68, v68, 0x3e0293ee, v148
	v_fmamk_f32 v69, v69, 0x3e0293ee, v148
	v_fmamk_f32 v70, v70, 0x3e0293ee, v148
	v_fmamk_f32 v71, v71, 0x3e0293ee, v148
	v_fmamk_f32 v72, v72, 0x3e0293ee, v148
	v_fmamk_f32 v73, v73, 0x3e0293ee, v148
	v_fmamk_f32 v74, v74, 0x3e0293ee, v148
	v_fmamk_f32 v75, v75, 0x3e0293ee, v148
	v_fmamk_f32 v76, v76, 0x3e0293ee, v148
	v_fmamk_f32 v77, v77, 0x3e0293ee, v148
	v_fmamk_f32 v78, v78, 0x3e0293ee, v148
	v_fmamk_f32 v79, v79, 0x3e0293ee, v148
	v_fmamk_f32 v80, v80, 0x3e0293ee, v148
	v_fmamk_f32 v81, v81, 0x3e0293ee, v148
	v_fmamk_f32 v82, v82, 0x3e0293ee, v148
	v_fmac_f32_e32 v148, 0x3e0293ee, v83
	v_exp_f32_e32 v83, v84
	v_exp_f32_e32 v84, v85
	v_exp_f32_e32 v85, v86
	v_add_f32_e32 v149, v84, v83
	v_exp_f32_e32 v86, v87
	v_add_f32_e32 v149, v85, v149
	v_exp_f32_e32 v87, v88
	v_add_f32_e32 v149, v86, v149
	v_exp_f32_e32 v88, v89
	v_add_f32_e32 v149, v87, v149
	v_exp_f32_e32 v89, v90
	v_add_f32_e32 v149, v88, v149
	v_exp_f32_e32 v90, v91
	v_add_f32_e32 v149, v89, v149
	v_exp_f32_e32 v91, v92
	v_add_f32_e32 v149, v90, v149
	v_exp_f32_e32 v92, v93
	v_add_f32_e32 v149, v91, v149
	v_exp_f32_e32 v93, v94
	v_add_f32_e32 v149, v92, v149
	v_exp_f32_e32 v94, v95
	v_add_f32_e32 v149, v93, v149
	v_exp_f32_e32 v95, v96
	v_add_f32_e32 v149, v94, v149
	v_exp_f32_e32 v96, v97
	v_add_f32_e32 v149, v95, v149
	v_exp_f32_e32 v97, v98
	v_add_f32_e32 v149, v96, v149
	v_exp_f32_e32 v98, v99
	v_add_f32_e32 v149, v97, v149
	v_exp_f32_e32 v99, v148
	v_add_f32_e32 v149, v98, v149
	v_exp_f32_e32 v68, v68
	v_exp_f32_e32 v69, v69
	v_add_f32_e32 v149, v68, v149
	v_exp_f32_e32 v70, v70
	v_add_f32_e32 v149, v69, v149
	v_exp_f32_e32 v71, v71
	v_add_f32_e32 v149, v70, v149
	v_exp_f32_e32 v72, v72
	v_add_f32_e32 v149, v71, v149
	v_exp_f32_e32 v73, v73
	v_add_f32_e32 v149, v72, v149
	v_exp_f32_e32 v74, v74
	v_add_f32_e32 v149, v73, v149
	v_exp_f32_e32 v75, v75
	v_add_f32_e32 v149, v74, v149
	v_exp_f32_e32 v76, v76
	v_add_f32_e32 v149, v75, v149
	v_exp_f32_e32 v77, v77
	v_add_f32_e32 v149, v76, v149
	v_exp_f32_e32 v78, v78
	v_add_f32_e32 v149, v77, v149
	v_exp_f32_e32 v79, v79
	v_add_f32_e32 v149, v78, v149
	v_exp_f32_e32 v80, v80
	v_add_f32_e32 v149, v79, v149
	v_exp_f32_e32 v81, v81
	v_add_f32_e32 v149, v80, v149
	v_exp_f32_e32 v82, v82
	v_add_f32_e32 v149, v81, v149
	v_mul_f32_e32 v150, 0x3e0293ee, v150
	v_add_f32_e32 v149, v82, v149
	v_exp_f32_e32 v150, v150
	v_add_f32_e32 v185, v99, v149
	v_cndmask_b32_e64 v184, v150, 1.0, vcc
	v_mov_b32_e32 v186, v185
	v_cvt_pk_bf16_f32 v148, v83, v84
	v_cvt_pk_bf16_f32 v149, v85, v86
	v_cvt_pk_bf16_f32 v150, v87, v88
	v_cvt_pk_bf16_f32 v151, v89, v90
	v_cvt_pk_bf16_f32 v152, v91, v92
	v_cvt_pk_bf16_f32 v153, v93, v94
	v_cvt_pk_bf16_f32 v154, v95, v96
	v_cvt_pk_bf16_f32 v155, v97, v98
	v_cvt_pk_bf16_f32 v156, v68, v69
	v_cvt_pk_bf16_f32 v157, v70, v71
	v_cvt_pk_bf16_f32 v158, v72, v73
	v_cvt_pk_bf16_f32 v159, v74, v75
	v_cvt_pk_bf16_f32 v160, v76, v77
	v_cvt_pk_bf16_f32 v161, v78, v79
	v_cvt_pk_bf16_f32 v162, v80, v81
	v_cvt_pk_bf16_f32 v163, v82, v99
	s_mov_b32 s53, s52
	s_nop 0
	v_permlane32_swap_b32_e32 v185, v186
	v_permlane32_swap_b32_e32 v148, v150
	v_permlane32_swap_b32_e32 v149, v151
	v_permlane32_swap_b32_e32 v152, v154
	v_permlane32_swap_b32_e32 v153, v155
	v_permlane32_swap_b32_e32 v156, v158
	v_permlane32_swap_b32_e32 v157, v159
	v_permlane32_swap_b32_e32 v160, v162
	v_permlane32_swap_b32_e32 v161, v163
	v_cmp_gt_f32_e32 vcc, 1.0, v184
	s_cbranch_vccz .LBB0_633
	s_and_saveexec_b64 s[16:17], s[38:39]
	ds_write_b32 v172, v184 offset:128
	s_or_b64 exec, exec, s[16:17]
	s_waitcnt lgkmcnt(0)
	v_add_u32_e32 v80, v171, v168
	ds_read_b128 v[68:71], v80 offset:224
	ds_read_b128 v[72:75], v80 offset:192
	ds_read_b128 v[76:79], v80 offset:160
	ds_read_b128 v[80:83], v80 offset:128
	s_waitcnt lgkmcnt(3)
	v_pk_mul_f32 v[16:17], v[16:17], v[68:69]
	s_waitcnt lgkmcnt(2)
	v_pk_mul_f32 v[12:13], v[12:13], v[72:73]
	s_waitcnt lgkmcnt(1)
	v_pk_mul_f32 v[8:9], v[8:9], v[76:77]
	v_pk_mul_f32 v[18:19], v[18:19], v[70:71]
	v_pk_mul_f32 v[14:15], v[14:15], v[74:75]
	v_pk_mul_f32 v[10:11], v[10:11], v[78:79]
	s_waitcnt lgkmcnt(0)
	v_pk_mul_f32 v[6:7], v[6:7], v[82:83]
	v_pk_mul_f32 v[4:5], v[4:5], v[80:81]
	v_pk_mul_f32 v[64:65], v[64:65], v[68:69]
	v_pk_mul_f32 v[60:61], v[60:61], v[72:73]
	v_pk_mul_f32 v[56:57], v[56:57], v[76:77]
	v_pk_mul_f32 v[66:67], v[66:67], v[70:71]
	v_pk_mul_f32 v[62:63], v[62:63], v[74:75]
	v_pk_mul_f32 v[58:59], v[58:59], v[78:79]
	v_pk_mul_f32 v[54:55], v[54:55], v[82:83]
	v_pk_mul_f32 v[52:53], v[52:53], v[80:81]
	v_pk_mul_f32 v[48:49], v[48:49], v[68:69]
	v_pk_mul_f32 v[44:45], v[44:45], v[72:73]
	v_pk_mul_f32 v[40:41], v[40:41], v[76:77]
	v_pk_mul_f32 v[50:51], v[50:51], v[70:71]
	v_pk_mul_f32 v[46:47], v[46:47], v[74:75]
	v_pk_mul_f32 v[42:43], v[42:43], v[78:79]
	v_pk_mul_f32 v[38:39], v[38:39], v[82:83]
	v_pk_mul_f32 v[36:37], v[36:37], v[80:81]
	v_pk_mul_f32 v[32:33], v[32:33], v[68:69]
	v_pk_mul_f32 v[28:29], v[28:29], v[72:73]
	v_pk_mul_f32 v[24:25], v[24:25], v[76:77]
	v_pk_mul_f32 v[34:35], v[34:35], v[70:71]
	v_pk_mul_f32 v[30:31], v[30:31], v[74:75]
	v_pk_mul_f32 v[26:27], v[26:27], v[78:79]
	v_pk_mul_f32 v[22:23], v[22:23], v[82:83]
	v_pk_mul_f32 v[20:21], v[20:21], v[80:81]
